# attention fast path with scalar v_add_f32 row sums instead of v_pk_add_f32 (docs: packed f32 beside MFMAs is an anti-lever), rest as comb10
# baseline (speedup 1.0000x reference)
; #define PG8_STAGE(bufoff, gbase, voff) do { _Pragma("unroll") for (int _i = 0; _i < 2; ++_i) \
;         __builtin_amdgcn_global_load_lds((const unsigned*)((const char*)(gbase) + (voff)[_i]), (PG8_LAS unsigned*)(lds + (bufoff) + ldsw + _i * 8192), 16, 0, 0); } while (0)
; #define PG8_LDA(dst, b, h) do { _Pragma("unroll") for (int m = 0; m < 4; ++m) _Pragma("unroll") for (int k = 0; k < 2; ++k) dst[m][k] = *(const PG8_LAS bf16x8*)(lds + PG8_SA(b, h) + aoff + m * 2048 + k * 1024); } while (0)
; #define PG8_LDB(dst, b, h) do { _Pragma("unroll") for (int n = 0; n < 2; ++n) _Pragma("unroll") for (int k = 0; k < 2; ++k) dst[n][k] = *(const PG8_LAS bf16x8*)(lds + PG8_SB(b, h) + boff + n * 2048 + k * 1024); } while (0)
; #define PG8_SCHED __builtin_amdgcn_sched_barrier(0)
; template <class Epi, class Sched, bool ALIGN_EPI = false, bool SP2 = false>
; __device__ __forceinline__ void gemm_phase(PG8_LAS unsigned char* lds, const Gemm g, const Sched& S, const Epi& E) {
;     ...
;         for (int t = 0; t < nt; t += 2) {
;             const bool last = (t == nt - 2);
;             const char* a1 = cA + (size_t)(t + 1) * kstep;
;             const char* a2 = last ? nA : cA + (size_t)(t + 2) * kstep; const char* b2 = last ? nB : cB + (size_t)(t + 2) * kstep;
;             const char* a3 = a2 + kstep; const char* b3 = b2 + kstep;
;             if (last && has_next) S.a_ready(nxt);
;             if constexpr (SP2) {
;             PG8_LDB(B0, 0, 0); PG8_LDB(B1, 0, 1); PG8_SCHED; PG8_LDA(At, 0, 0); PG8_STAGE(PG8_SA(1, 1), a1 + hstep, voffA);
;     ...
; #pragma unroll
;         for (int a = 0; a < 2; ++a)
; #pragma unroll
;             for (int b = 0; b < 2; ++b)
; #pragma unroll
;                 for (int m = 0; m < 4; ++m)
; #pragma unroll
;                     for (int n = 0; n < 2; ++n) acc[a][b][m][n] = (f32x4){0.f, 0.f, 0.f, 0.f};
.LBB0_524:
	s_ashr_i32 s23, s22, 31
	s_lshl_b64 s[24:25], s[22:23], 19
	s_add_u32 s24, s62, s24
	s_addc_u32 s25, s63, s25
	s_and_b64 s[26:27], s[0:1], exec
	s_cselect_b32 s3, s25, s31
	s_cselect_b32 s23, s24, s30
	s_ashr_i32 s21, s20, 31
	s_lshl_b64 s[26:27], s[20:21], 19
	s_add_u32 s26, s6, s26
	s_addc_u32 s27, s7, s27
	s_and_b64 s[36:37], s[0:1], exec
	s_cselect_b32 s21, s27, s35
	s_cselect_b32 s50, s26, s34
	s_add_u32 s30, s30, 0x40080
	s_addc_u32 s31, s31, 0
	s_add_u32 s51, s34, 0x100
	v_mov_b32_e32 v0, 0
	s_addc_u32 s52, s35, 0
	s_mov_b32 s53, -2
	v_mov_b32_e32 v1, v0
	v_mov_b32_e32 v2, v0
	v_mov_b32_e32 v3, v0
	v_mov_b32_e32 v4, v0
	v_mov_b32_e32 v5, v0
	v_mov_b32_e32 v6, v0
	v_mov_b32_e32 v7, v0
	v_mov_b32_e32 v8, v0
	v_mov_b32_e32 v9, v0
	v_mov_b32_e32 v10, v0
	v_mov_b32_e32 v11, v0
	v_mov_b32_e32 v12, v0
	v_mov_b32_e32 v13, v0
	v_mov_b32_e32 v14, v0
	v_mov_b32_e32 v15, v0
	v_mov_b32_e32 v16, v0
	v_mov_b32_e32 v17, v0
	v_mov_b32_e32 v18, v0
	v_mov_b32_e32 v19, v0
	v_mov_b32_e32 v20, v0
	v_mov_b32_e32 v21, v0
	v_mov_b32_e32 v22, v0
	v_mov_b32_e32 v23, v0
	v_mov_b32_e32 v24, v0
	v_mov_b32_e32 v25, v0
	v_mov_b32_e32 v26, v0
	v_mov_b32_e32 v27, v0
	v_mov_b32_e32 v28, v0
	v_mov_b32_e32 v29, v0
	v_mov_b32_e32 v30, v0
	v_mov_b32_e32 v31, v0
	v_mov_b32_e32 v60, v0
	v_mov_b32_e32 v61, v0
	v_mov_b32_e32 v62, v0
	v_mov_b32_e32 v63, v0
	v_mov_b32_e32 v68, v0
	v_mov_b32_e32 v69, v0
	v_mov_b32_e32 v70, v0
	v_mov_b32_e32 v71, v0
	v_mov_b32_e32 v72, v0
	v_mov_b32_e32 v73, v0
	v_mov_b32_e32 v74, v0
	v_mov_b32_e32 v75, v0
	v_mov_b32_e32 v76, v0
	v_mov_b32_e32 v77, v0
	v_mov_b32_e32 v78, v0
	v_mov_b32_e32 v79, v0
	v_mov_b32_e32 v80, v0
	v_mov_b32_e32 v81, v0
	v_mov_b32_e32 v82, v0
	v_mov_b32_e32 v83, v0
	v_mov_b32_e32 v84, v0
	v_mov_b32_e32 v85, v0
	v_mov_b32_e32 v86, v0
	v_mov_b32_e32 v87, v0
	v_mov_b32_e32 v88, v0
	v_mov_b32_e32 v89, v0
	v_mov_b32_e32 v90, v0
	v_mov_b32_e32 v91, v0
	v_mov_b32_e32 v92, v0
	v_mov_b32_e32 v93, v0
	v_mov_b32_e32 v94, v0
	v_mov_b32_e32 v95, v0
	v_mov_b32_e32 v32, v0
	v_mov_b32_e32 v33, v0
	v_mov_b32_e32 v34, v0
	v_mov_b32_e32 v35, v0
	v_mov_b32_e32 v36, v0
	v_mov_b32_e32 v37, v0
	v_mov_b32_e32 v38, v0
	v_mov_b32_e32 v39, v0
	v_mov_b32_e32 v40, v0
	v_mov_b32_e32 v41, v0
	v_mov_b32_e32 v42, v0
	v_mov_b32_e32 v43, v0
	v_mov_b32_e32 v44, v0
	v_mov_b32_e32 v45, v0
	v_mov_b32_e32 v46, v0
	v_mov_b32_e32 v47, v0
	v_mov_b32_e32 v48, v0
	v_mov_b32_e32 v49, v0
	v_mov_b32_e32 v50, v0
	v_mov_b32_e32 v51, v0
	v_mov_b32_e32 v52, v0
	v_mov_b32_e32 v53, v0
	v_mov_b32_e32 v54, v0
	v_mov_b32_e32 v55, v0
	v_mov_b32_e32 v56, v0
	v_mov_b32_e32 v57, v0
	v_mov_b32_e32 v58, v0
	v_mov_b32_e32 v59, v0
	v_mov_b32_e32 v64, v0
	v_mov_b32_e32 v65, v0
	v_mov_b32_e32 v66, v0
	v_mov_b32_e32 v67, v0
	v_mov_b32_e32 v96, v0
	v_mov_b32_e32 v97, v0
	v_mov_b32_e32 v98, v0
	v_mov_b32_e32 v99, v0
	v_mov_b32_e32 v100, v0
	v_mov_b32_e32 v101, v0
	v_mov_b32_e32 v102, v0
	v_mov_b32_e32 v103, v0
	v_mov_b32_e32 v104, v0
	v_mov_b32_e32 v105, v0
	v_mov_b32_e32 v106, v0
	v_mov_b32_e32 v107, v0
	v_mov_b32_e32 v108, v0
	v_mov_b32_e32 v109, v0
	v_mov_b32_e32 v110, v0
	v_mov_b32_e32 v111, v0
	v_mov_b32_e32 v112, v0
	v_mov_b32_e32 v113, v0
	v_mov_b32_e32 v114, v0
	v_mov_b32_e32 v115, v0
	v_mov_b32_e32 v116, v0
	v_mov_b32_e32 v117, v0
	v_mov_b32_e32 v118, v0
	v_mov_b32_e32 v119, v0
	v_mov_b32_e32 v120, v0
	v_mov_b32_e32 v121, v0
	v_mov_b32_e32 v122, v0
	v_mov_b32_e32 v123, v0
	v_mov_b32_e32 v124, v0
	v_mov_b32_e32 v125, v0
	v_mov_b32_e32 v126, v0
	v_mov_b32_e32 v127, v0
	v_lshl_add_u32 v246, s2, 8, v153
	v_ashrrev_i32_e32 v247, 31, v246
	v_lshl_add_u64 v[248:249], v[246:247], 2, s[4:5]
	global_load_dword v230, v[248:249], off
	global_load_dword v232, v[248:249], off offset:64
	global_load_dword v234, v[248:249], off offset:128
	global_load_dword v236, v[248:249], off offset:192
	global_load_dword v238, v[248:249], off offset:512
	global_load_dword v240, v[248:249], off offset:576
	global_load_dword v242, v[248:249], off offset:640
	global_load_dword v244, v[248:249], off offset:704
	s_cmp_eq_u32 s41, 1
	s_cselect_b32 s101, 0x7fffffff, -2

; #define PG8_STAGE(bufoff, gbase, voff) do { _Pragma("unroll") for (int _i = 0; _i < 2; ++_i) \
;         __builtin_amdgcn_global_load_lds((const unsigned*)((const char*)(gbase) + (voff)[_i]), (PG8_LAS unsigned*)(lds + (bufoff) + ldsw + _i * 8192), 16, 0, 0); } while (0)
; #define PG8_LDA(dst, b, h) do { _Pragma("unroll") for (int m = 0; m < 4; ++m) _Pragma("unroll") for (int k = 0; k < 2; ++k) dst[m][k] = *(const PG8_LAS bf16x8*)(lds + PG8_SA(b, h) + aoff + m * 2048 + k * 1024); } while (0)
; #define PG8_LDB(dst, b, h) do { _Pragma("unroll") for (int n = 0; n < 2; ++n) _Pragma("unroll") for (int k = 0; k < 2; ++k) dst[n][k] = *(const PG8_LAS bf16x8*)(lds + PG8_SB(b, h) + boff + n * 2048 + k * 1024); } while (0)
; #define PG8_SCHED __builtin_amdgcn_sched_barrier(0)
; template <class Epi, class Sched, bool ALIGN_EPI = false, bool SP2 = false>
; __device__ __forceinline__ void gemm_phase(PG8_LAS unsigned char* lds, const Gemm g, const Sched& S, const Epi& E) {
;     ...
;         for (int t = 0; t < nt; t += 2) {
;             const bool last = (t == nt - 2);
;             const char* a1 = cA + (size_t)(t + 1) * kstep;
;             const char* a2 = last ? nA : cA + (size_t)(t + 2) * kstep; const char* b2 = last ? nB : cB + (size_t)(t + 2) * kstep;
;             const char* a3 = a2 + kstep; const char* b3 = b2 + kstep;
;             if (last && has_next) S.a_ready(nxt);
;             if constexpr (SP2) {
;             PG8_LDB(B0, 0, 0); PG8_LDB(B1, 0, 1); PG8_SCHED; PG8_LDA(At, 0, 0); PG8_STAGE(PG8_SA(1, 1), a1 + hstep, voffA);
;     ...
; #pragma unroll
;         for (int a = 0; a < 2; ++a)
; #pragma unroll
;             for (int b = 0; b < 2; ++b)
; #pragma unroll
;                 for (int m = 0; m < 4; ++m)
; #pragma unroll
;                     for (int n = 0; n < 2; ++n) acc[a][b][m][n] = (f32x4){0.f, 0.f, 0.f, 0.f};
.LBB0_1145:
	s_ashr_i32 s19, s18, 31
	s_lshl_b64 s[20:21], s[18:19], 19
	s_add_u32 s20, s80, s20
	s_addc_u32 s21, s81, s21
	s_and_b64 s[22:23], s[0:1], exec
	s_cselect_b32 s3, s21, s27
	s_cselect_b32 s19, s20, s26
	s_ashr_i32 s17, s16, 31
	s_lshl_b64 s[22:23], s[16:17], 19
	s_add_u32 s22, s56, s22
	s_addc_u32 s23, s57, s23
	s_and_b64 s[30:31], s[0:1], exec
	s_cselect_b32 s17, s23, s29
	s_cselect_b32 s47, s22, s28
	s_add_u32 s26, s26, 0x40080
	s_addc_u32 s27, s27, 0
	s_add_u32 s48, s28, 0x100
	v_mov_b32_e32 v0, 0
	s_addc_u32 s49, s29, 0
	s_mov_b32 s50, -2
	v_mov_b32_e32 v1, v0
	v_mov_b32_e32 v2, v0
	v_mov_b32_e32 v3, v0
	v_mov_b32_e32 v8, v0
	v_mov_b32_e32 v9, v0
	v_mov_b32_e32 v10, v0
	v_mov_b32_e32 v11, v0
	v_mov_b32_e32 v16, v0
	v_mov_b32_e32 v17, v0
	v_mov_b32_e32 v18, v0
	v_mov_b32_e32 v19, v0
	v_mov_b32_e32 v24, v0
	v_mov_b32_e32 v25, v0
	v_mov_b32_e32 v26, v0
	v_mov_b32_e32 v27, v0
	v_mov_b32_e32 v32, v0
	v_mov_b32_e32 v33, v0
	v_mov_b32_e32 v34, v0
	v_mov_b32_e32 v35, v0
	v_mov_b32_e32 v40, v0
	v_mov_b32_e32 v41, v0
	v_mov_b32_e32 v42, v0
	v_mov_b32_e32 v43, v0
	v_mov_b32_e32 v48, v0
	v_mov_b32_e32 v49, v0
	v_mov_b32_e32 v50, v0
	v_mov_b32_e32 v51, v0
	v_mov_b32_e32 v56, v0
	v_mov_b32_e32 v57, v0
	v_mov_b32_e32 v58, v0
	v_mov_b32_e32 v59, v0
	v_mov_b32_e32 v4, v0
	v_mov_b32_e32 v5, v0
	v_mov_b32_e32 v6, v0
	v_mov_b32_e32 v7, v0
	v_mov_b32_e32 v12, v0
	v_mov_b32_e32 v13, v0
	v_mov_b32_e32 v14, v0
	v_mov_b32_e32 v15, v0
	v_mov_b32_e32 v20, v0
	v_mov_b32_e32 v21, v0
	v_mov_b32_e32 v22, v0
	v_mov_b32_e32 v23, v0
	v_mov_b32_e32 v28, v0
	v_mov_b32_e32 v29, v0
	v_mov_b32_e32 v30, v0
	v_mov_b32_e32 v31, v0
	v_mov_b32_e32 v36, v0
	v_mov_b32_e32 v37, v0
	v_mov_b32_e32 v38, v0
	v_mov_b32_e32 v39, v0
	v_mov_b32_e32 v44, v0
	v_mov_b32_e32 v45, v0
	v_mov_b32_e32 v46, v0
	v_mov_b32_e32 v47, v0
	v_mov_b32_e32 v52, v0
	v_mov_b32_e32 v53, v0
	v_mov_b32_e32 v54, v0
	v_mov_b32_e32 v55, v0
	v_mov_b32_e32 v60, v0
	v_mov_b32_e32 v61, v0
	v_mov_b32_e32 v62, v0
	v_mov_b32_e32 v63, v0
	v_mov_b32_e32 v64, v0
	v_mov_b32_e32 v65, v0
	v_mov_b32_e32 v66, v0
	v_mov_b32_e32 v67, v0
	v_mov_b32_e32 v72, v0
	v_mov_b32_e32 v73, v0
	v_mov_b32_e32 v74, v0
	v_mov_b32_e32 v75, v0
	v_mov_b32_e32 v80, v0
	v_mov_b32_e32 v81, v0
	v_mov_b32_e32 v82, v0
	v_mov_b32_e32 v83, v0
	v_mov_b32_e32 v88, v0
	v_mov_b32_e32 v89, v0
	v_mov_b32_e32 v90, v0
	v_mov_b32_e32 v91, v0
	v_mov_b32_e32 v96, v0
	v_mov_b32_e32 v97, v0
	v_mov_b32_e32 v98, v0
	v_mov_b32_e32 v99, v0
	v_mov_b32_e32 v104, v0
	v_mov_b32_e32 v105, v0
	v_mov_b32_e32 v106, v0
	v_mov_b32_e32 v107, v0
	v_mov_b32_e32 v112, v0
	v_mov_b32_e32 v113, v0
	v_mov_b32_e32 v114, v0
	v_mov_b32_e32 v115, v0
	v_mov_b32_e32 v120, v0
	v_mov_b32_e32 v121, v0
	v_mov_b32_e32 v122, v0
	v_mov_b32_e32 v123, v0
	v_mov_b32_e32 v68, v0
	v_mov_b32_e32 v69, v0
	v_mov_b32_e32 v70, v0
	v_mov_b32_e32 v71, v0
	v_mov_b32_e32 v76, v0
	v_mov_b32_e32 v77, v0
	v_mov_b32_e32 v78, v0
	v_mov_b32_e32 v79, v0
	v_mov_b32_e32 v84, v0
	v_mov_b32_e32 v85, v0
	v_mov_b32_e32 v86, v0
	v_mov_b32_e32 v87, v0
	v_mov_b32_e32 v92, v0
	v_mov_b32_e32 v93, v0
	v_mov_b32_e32 v94, v0
	v_mov_b32_e32 v95, v0
	v_mov_b32_e32 v100, v0
	v_mov_b32_e32 v101, v0
	v_mov_b32_e32 v102, v0
	v_mov_b32_e32 v103, v0
	v_mov_b32_e32 v108, v0
	v_mov_b32_e32 v109, v0
	v_mov_b32_e32 v110, v0
	v_mov_b32_e32 v111, v0
	v_mov_b32_e32 v116, v0
	v_mov_b32_e32 v117, v0
	v_mov_b32_e32 v118, v0
	v_mov_b32_e32 v119, v0
	v_mov_b32_e32 v124, v0
	v_mov_b32_e32 v125, v0
	v_mov_b32_e32 v126, v0
	v_mov_b32_e32 v127, v0
	v_lshl_add_u32 v246, s2, 8, v149
	v_ashrrev_i32_e32 v247, 31, v246
	v_lshl_add_u64 v[248:249], v[246:247], 2, s[4:5]
	global_load_dword v230, v[248:249], off
	global_load_dword v232, v[248:249], off offset:64
	global_load_dword v234, v[248:249], off offset:128
	global_load_dword v236, v[248:249], off offset:192
	global_load_dword v238, v[248:249], off offset:512
	global_load_dword v240, v[248:249], off offset:576
	global_load_dword v242, v[248:249], off offset:640
	global_load_dword v244, v[248:249], off offset:704
	s_cmp_eq_u32 s37, 1
	s_cselect_b32 s101, 0x7fffffff, -2
